# EpiResid epilogue in two passes: all XB stores first, then sum of squares + lane reduction + ssq stores (the stores get that time to drain before the next K-loop's first wait)
# speedup vs baseline: 1.0167x; 1.0167x over previous
; __device__ __forceinline__ float bf_lo(unsigned u) { return __uint_as_float(u << 16); }
; __device__ __forceinline__ float bf_hi(unsigned u) { return __uint_as_float(u & 0xffff0000u); }
; __device__ __forceinline__ unsigned pk_bf16(float lo, float hi) { const f32x2 v = {lo, hi}; const bf16x2_t b = __builtin_convertvector(v, bf16x2_t); return __builtin_bit_cast(unsigned, b); }
;     __device__ __forceinline__ void operator()(const f32x4 (&acc)[2][2][4][2], const pg8::Unit& u, int wr, int wc, int fr, int fq) const {
;     ...
;         const int row0 = u.pm * 256 + wr * 64 + fr, col0 = u.pn * 256 + wc * 32 + 4 * fq;
;         const bool rf32 = (rp != nullptr) && (u.pm < MP / 256);
; #pragma unroll
;         for (int ai = 0; ai < 2; ++ai)
; #pragma unroll
;             for (int m = 0; m < 4; ++m) {
;                 const int row = row0 + ai * 128 + m * 16; const size_t off = (size_t)row * DM + col0; float q = 0.f;
;                 f32x4 r4[2][2];
;                 if (rf32) {
; #pragma unroll
;                     for (int bj = 0; bj < 2; ++bj)
; #pragma unroll
;                         for (int n = 0; n < 2; ++n) r4[bj][n] = *(const f32x4*)(rp + off + bj * 128 + n * 16);
;                 } else {
; #pragma unroll
;                     for (int bj = 0; bj < 2; ++bj)
; #pragma unroll
;                         for (int n = 0; n < 2; ++n) { const u32x2 w = *(const u32x2*)(XB + off + bj * 128 + n * 16); r4[bj][n] = (f32x4){bf_lo(w.x), bf_hi(w.x), bf_lo(w.y), bf_hi(w.y)}; }
;                 }
; #pragma unroll
;                 for (int bj = 0; bj < 2; ++bj)
; #pragma unroll
;                     for (int n = 0; n < 2; ++n) { const f32x4 x4 = r4[bj][n] + acc[ai][bj][m][n];
;                         q += (x4[0] * x4[0] + x4[1] * x4[1]) + (x4[2] * x4[2] + x4[3] * x4[3]);
;                         u32x2 w; w.x = pk_bf16(x4[0], x4[1]); w.y = pk_bf16(x4[2], x4[3]); *(u32x2*)(XB + off + bj * 128 + n * 16) = w; }
.LBB0_1683:
	s_lshl_b32 s4, s51, 8
	v_mov_b32_e32 v158, v1
	s_add_i32 s4, s4, s46
	s_lshl_b32 s28, s50, 2
	v_add_u32_e32 v160, s4, v158
	v_ashrrev_i32_e32 v161, 31, v160
	v_lshl_or_b32 v158, s50, 8, v163
	v_lshlrev_b64 v[166:167], 11, v[160:161]
	v_ashrrev_i32_e32 v159, 31, v158
	v_lshl_add_u64 v[166:167], s[14:15], 0, v[166:167]
	v_lshl_add_u64 v[166:167], v[158:159], 1, v[166:167]
	s_ashr_i32 s29, s28, 31
	v_lshlrev_b32_e32 v252, 11, v160
	v_lshl_add_u32 v252, v158, 1, v252
	v_bfe_u32 v253, v190, 4, 1
	v_mul_u32_u24_e32 v253, 24, v253
	v_add_u32_e32 v252, v252, v253
	s_lshl_b32 s88, s45, 2
	v_lshl_add_u32 v189, v160, 6, s88
	v_lshl_add_u32 v189, s28, 2, v189
	global_load_dwordx4 v[204:207], v252, s[14:15]
	global_load_dwordx4 v[208:211], v252, s[14:15] offset:256
	v_add_u32_e32 v253, 0x8000, v252
	global_load_dwordx4 v[212:215], v253, s[14:15]
	global_load_dwordx4 v[216:219], v253, s[14:15] offset:256
	v_add_u32_e32 v253, 0x10000, v252
	global_load_dwordx4 v[220:223], v253, s[14:15]
	global_load_dwordx4 v[224:227], v253, s[14:15] offset:256
	v_add_u32_e32 v253, 0x18000, v252
	global_load_dwordx4 v[228:231], v253, s[14:15]
	global_load_dwordx4 v[232:235], v253, s[14:15] offset:256
	v_add_u32_e32 v253, 0x40000, v252
	global_load_dwordx4 v[236:239], v253, s[14:15]
	global_load_dwordx4 v[240:243], v253, s[14:15] offset:256
	v_add_u32_e32 v253, 0x48000, v252
	global_load_dwordx4 v[244:247], v253, s[14:15]
	global_load_dwordx4 v[248:251], v253, s[14:15] offset:256
	s_waitcnt vmcnt(10)
	v_permlane16_swap_b32_e32 v204, v206
	v_permlane16_swap_b32_e32 v205, v207
	v_permlane16_swap_b32_e32 v208, v210
	v_permlane16_swap_b32_e32 v209, v211
	v_lshlrev_b32_e32 v166, 16, v204
	v_and_b32_e32 v167, 0xffff0000, v204
	v_lshlrev_b32_e32 v168, 16, v205
	v_and_b32_e32 v169, 0xffff0000, v205
	v_lshlrev_b32_e32 v170, 16, v206
	v_and_b32_e32 v171, 0xffff0000, v206
	v_lshlrev_b32_e32 v172, 16, v207
	v_and_b32_e32 v173, 0xffff0000, v207
	v_lshlrev_b32_e32 v174, 16, v208
	v_and_b32_e32 v175, 0xffff0000, v208
	v_lshlrev_b32_e32 v176, 16, v209
	v_and_b32_e32 v177, 0xffff0000, v209
	v_lshlrev_b32_e32 v178, 16, v210
	v_and_b32_e32 v179, 0xffff0000, v210
	v_lshlrev_b32_e32 v180, 16, v211
	v_and_b32_e32 v181, 0xffff0000, v211
	v_pk_add_f32 v[126:127], v[126:127], v[166:167]
	v_pk_add_f32 v[128:129], v[128:129], v[168:169]
	v_pk_add_f32 v[122:123], v[122:123], v[170:171]
	v_pk_add_f32 v[124:125], v[124:125], v[172:173]
	v_pk_add_f32 v[118:119], v[118:119], v[174:175]
	v_pk_add_f32 v[120:121], v[120:121], v[176:177]
	v_pk_add_f32 v[114:115], v[114:115], v[178:179]
	v_pk_add_f32 v[116:117], v[116:117], v[180:181]
	v_add_u32_e32 v253, 0x50000, v252
	global_load_dwordx4 v[204:207], v253, s[14:15]
	global_load_dwordx4 v[208:211], v253, s[14:15] offset:256
	v_cvt_pk_bf16_f32 v166, v126, v127
	v_cvt_pk_bf16_f32 v167, v128, v129
	v_cvt_pk_bf16_f32 v168, v122, v123
	v_cvt_pk_bf16_f32 v169, v124, v125
	v_cvt_pk_bf16_f32 v170, v118, v119
	v_cvt_pk_bf16_f32 v171, v120, v121
	v_cvt_pk_bf16_f32 v172, v114, v115
	v_cvt_pk_bf16_f32 v173, v116, v117
	s_nop 1
	v_permlane16_swap_b32_e32 v166, v168
	v_permlane16_swap_b32_e32 v167, v169
	v_permlane16_swap_b32_e32 v170, v172
	v_permlane16_swap_b32_e32 v171, v173
	global_store_dwordx4 v252, v[166:169], s[14:15]
	global_store_dwordx4 v252, v[170:173], s[14:15] offset:256
	s_nop 1
	s_waitcnt vmcnt(12)
	v_permlane16_swap_b32_e32 v212, v214
	v_permlane16_swap_b32_e32 v213, v215
	v_permlane16_swap_b32_e32 v216, v218
	v_permlane16_swap_b32_e32 v217, v219
	v_lshlrev_b32_e32 v166, 16, v212
	v_and_b32_e32 v167, 0xffff0000, v212
	v_lshlrev_b32_e32 v168, 16, v213
	v_and_b32_e32 v169, 0xffff0000, v213
	v_lshlrev_b32_e32 v170, 16, v214
	v_and_b32_e32 v171, 0xffff0000, v214
	v_lshlrev_b32_e32 v172, 16, v215
	v_and_b32_e32 v173, 0xffff0000, v215
	v_lshlrev_b32_e32 v174, 16, v216
	v_and_b32_e32 v175, 0xffff0000, v216
	v_lshlrev_b32_e32 v176, 16, v217
	v_and_b32_e32 v177, 0xffff0000, v217
	v_lshlrev_b32_e32 v178, 16, v218
	v_and_b32_e32 v179, 0xffff0000, v218
	v_lshlrev_b32_e32 v180, 16, v219
	v_and_b32_e32 v181, 0xffff0000, v219
	v_pk_add_f32 v[110:111], v[110:111], v[166:167]
	v_pk_add_f32 v[112:113], v[112:113], v[168:169]
	v_pk_add_f32 v[106:107], v[106:107], v[170:171]
	v_pk_add_f32 v[108:109], v[108:109], v[172:173]
	v_pk_add_f32 v[102:103], v[102:103], v[174:175]
	v_pk_add_f32 v[104:105], v[104:105], v[176:177]
	v_pk_add_f32 v[98:99], v[98:99], v[178:179]
	v_pk_add_f32 v[100:101], v[100:101], v[180:181]
	v_add_u32_e32 v253, 0x58000, v252
	global_load_dwordx4 v[212:215], v253, s[14:15]
	global_load_dwordx4 v[216:219], v253, s[14:15] offset:256
	v_cvt_pk_bf16_f32 v166, v110, v111
	v_cvt_pk_bf16_f32 v167, v112, v113
	v_cvt_pk_bf16_f32 v168, v106, v107
	v_cvt_pk_bf16_f32 v169, v108, v109
	v_cvt_pk_bf16_f32 v170, v102, v103
	v_cvt_pk_bf16_f32 v171, v104, v105
	v_cvt_pk_bf16_f32 v172, v98, v99
	v_cvt_pk_bf16_f32 v173, v100, v101
	v_add_u32_e32 v253, 0x8000, v252
	s_nop 1
	v_permlane16_swap_b32_e32 v166, v168
	v_permlane16_swap_b32_e32 v167, v169
	v_permlane16_swap_b32_e32 v170, v172
	v_permlane16_swap_b32_e32 v171, v173
	global_store_dwordx4 v253, v[166:169], s[14:15]
	global_store_dwordx4 v253, v[170:173], s[14:15] offset:256
	s_nop 1
	s_waitcnt vmcnt(14)
; __device__ __forceinline__ float bf_lo(unsigned u) { return __uint_as_float(u << 16); }
; __device__ __forceinline__ float bf_hi(unsigned u) { return __uint_as_float(u & 0xffff0000u); }
; __device__ __forceinline__ unsigned pk_bf16(float lo, float hi) { const f32x2 v = {lo, hi}; const bf16x2_t b = __builtin_convertvector(v, bf16x2_t); return __builtin_bit_cast(unsigned, b); }
;     __device__ __forceinline__ void operator()(const f32x4 (&acc)[2][2][4][2], const pg8::Unit& u, int wr, int wc, int fr, int fq) const {
;     ...
; #pragma unroll
;                     for (int bj = 0; bj < 2; ++bj)
; #pragma unroll
;                         for (int n = 0; n < 2; ++n) { const u32x2 w = *(const u32x2*)(XB + off + bj * 128 + n * 16); r4[bj][n] = (f32x4){bf_lo(w.x), bf_hi(w.x), bf_lo(w.y), bf_hi(w.y)}; }
;                 }
; #pragma unroll
;                 for (int bj = 0; bj < 2; ++bj)
; #pragma unroll
;                     for (int n = 0; n < 2; ++n) { const f32x4 x4 = r4[bj][n] + acc[ai][bj][m][n];
;                         q += (x4[0] * x4[0] + x4[1] * x4[1]) + (x4[2] * x4[2] + x4[3] * x4[3]);
;                         u32x2 w; w.x = pk_bf16(x4[0], x4[1]); w.y = pk_bf16(x4[2], x4[3]); *(u32x2*)(XB + off + bj * 128 + n * 16) = w; }
	v_permlane16_swap_b32_e32 v220, v222
	v_permlane16_swap_b32_e32 v221, v223
	v_permlane16_swap_b32_e32 v224, v226
	v_permlane16_swap_b32_e32 v225, v227
	v_lshlrev_b32_e32 v166, 16, v220
	v_and_b32_e32 v167, 0xffff0000, v220
	v_lshlrev_b32_e32 v168, 16, v221
	v_and_b32_e32 v169, 0xffff0000, v221
	v_lshlrev_b32_e32 v170, 16, v222
	v_and_b32_e32 v171, 0xffff0000, v222
	v_lshlrev_b32_e32 v172, 16, v223
	v_and_b32_e32 v173, 0xffff0000, v223
	v_lshlrev_b32_e32 v174, 16, v224
	v_and_b32_e32 v175, 0xffff0000, v224
	v_lshlrev_b32_e32 v176, 16, v225
	v_and_b32_e32 v177, 0xffff0000, v225
	v_lshlrev_b32_e32 v178, 16, v226
	v_and_b32_e32 v179, 0xffff0000, v226
	v_lshlrev_b32_e32 v180, 16, v227
	v_and_b32_e32 v181, 0xffff0000, v227
	v_pk_add_f32 v[94:95], v[94:95], v[166:167]
	v_pk_add_f32 v[96:97], v[96:97], v[168:169]
	v_pk_add_f32 v[90:91], v[90:91], v[170:171]
	v_pk_add_f32 v[92:93], v[92:93], v[172:173]
	v_pk_add_f32 v[86:87], v[86:87], v[174:175]
	v_pk_add_f32 v[88:89], v[88:89], v[176:177]
	v_pk_add_f32 v[82:83], v[82:83], v[178:179]
	v_pk_add_f32 v[84:85], v[84:85], v[180:181]
	v_cvt_pk_bf16_f32 v166, v94, v95
	v_cvt_pk_bf16_f32 v167, v96, v97
	v_cvt_pk_bf16_f32 v168, v90, v91
	v_cvt_pk_bf16_f32 v169, v92, v93
	v_cvt_pk_bf16_f32 v170, v86, v87
	v_cvt_pk_bf16_f32 v171, v88, v89
	v_cvt_pk_bf16_f32 v172, v82, v83
	v_cvt_pk_bf16_f32 v173, v84, v85
	v_add_u32_e32 v253, 0x10000, v252
	s_nop 1
	v_permlane16_swap_b32_e32 v166, v168
	v_permlane16_swap_b32_e32 v167, v169
	v_permlane16_swap_b32_e32 v170, v172
	v_permlane16_swap_b32_e32 v171, v173
	global_store_dwordx4 v253, v[166:169], s[14:15]
	global_store_dwordx4 v253, v[170:173], s[14:15] offset:256
	s_nop 1
	s_waitcnt vmcnt(14)
	v_permlane16_swap_b32_e32 v228, v230
	v_permlane16_swap_b32_e32 v229, v231
	v_permlane16_swap_b32_e32 v232, v234
	v_permlane16_swap_b32_e32 v233, v235
	v_lshlrev_b32_e32 v166, 16, v228
	v_and_b32_e32 v167, 0xffff0000, v228
	v_lshlrev_b32_e32 v168, 16, v229
	v_and_b32_e32 v169, 0xffff0000, v229
	v_lshlrev_b32_e32 v170, 16, v230
	v_and_b32_e32 v171, 0xffff0000, v230
	v_lshlrev_b32_e32 v172, 16, v231
	v_and_b32_e32 v173, 0xffff0000, v231
	v_lshlrev_b32_e32 v174, 16, v232
	v_and_b32_e32 v175, 0xffff0000, v232
	v_lshlrev_b32_e32 v176, 16, v233
	v_and_b32_e32 v177, 0xffff0000, v233
	v_lshlrev_b32_e32 v178, 16, v234
	v_and_b32_e32 v179, 0xffff0000, v234
	v_lshlrev_b32_e32 v180, 16, v235
	v_and_b32_e32 v181, 0xffff0000, v235
	v_pk_add_f32 v[78:79], v[78:79], v[166:167]
	v_pk_add_f32 v[80:81], v[80:81], v[168:169]
	v_pk_add_f32 v[74:75], v[74:75], v[170:171]
	v_pk_add_f32 v[76:77], v[76:77], v[172:173]
	v_pk_add_f32 v[70:71], v[70:71], v[174:175]
	v_pk_add_f32 v[72:73], v[72:73], v[176:177]
	v_pk_add_f32 v[66:67], v[66:67], v[178:179]
	v_pk_add_f32 v[68:69], v[68:69], v[180:181]
	v_cvt_pk_bf16_f32 v166, v78, v79
	v_cvt_pk_bf16_f32 v167, v80, v81
	v_cvt_pk_bf16_f32 v168, v74, v75
	v_cvt_pk_bf16_f32 v169, v76, v77
	v_cvt_pk_bf16_f32 v170, v70, v71
	v_cvt_pk_bf16_f32 v171, v72, v73
	v_cvt_pk_bf16_f32 v172, v66, v67
	v_cvt_pk_bf16_f32 v173, v68, v69
	v_add_u32_e32 v253, 0x18000, v252
	s_nop 1
	v_permlane16_swap_b32_e32 v166, v168
	v_permlane16_swap_b32_e32 v167, v169
	v_permlane16_swap_b32_e32 v170, v172
	v_permlane16_swap_b32_e32 v171, v173
	global_store_dwordx4 v253, v[166:169], s[14:15]
	global_store_dwordx4 v253, v[170:173], s[14:15] offset:256
	s_nop 1
	s_waitcnt vmcnt(14)
	v_permlane16_swap_b32_e32 v236, v238
	v_permlane16_swap_b32_e32 v237, v239
	v_permlane16_swap_b32_e32 v240, v242
	v_permlane16_swap_b32_e32 v241, v243
	v_lshlrev_b32_e32 v166, 16, v236
	v_and_b32_e32 v167, 0xffff0000, v236
	v_lshlrev_b32_e32 v168, 16, v237
	v_and_b32_e32 v169, 0xffff0000, v237
	v_lshlrev_b32_e32 v170, 16, v238
	v_and_b32_e32 v171, 0xffff0000, v238
	v_lshlrev_b32_e32 v172, 16, v239
	v_and_b32_e32 v173, 0xffff0000, v239
	v_lshlrev_b32_e32 v174, 16, v240
	v_and_b32_e32 v175, 0xffff0000, v240
	v_lshlrev_b32_e32 v176, 16, v241
	v_and_b32_e32 v177, 0xffff0000, v241
	v_lshlrev_b32_e32 v178, 16, v242
	v_and_b32_e32 v179, 0xffff0000, v242
	v_lshlrev_b32_e32 v180, 16, v243
	v_and_b32_e32 v181, 0xffff0000, v243
	v_pk_add_f32 v[62:63], v[62:63], v[166:167]
	v_pk_add_f32 v[64:65], v[64:65], v[168:169]
	v_pk_add_f32 v[58:59], v[58:59], v[170:171]
	v_pk_add_f32 v[60:61], v[60:61], v[172:173]
	v_pk_add_f32 v[54:55], v[54:55], v[174:175]
	v_pk_add_f32 v[56:57], v[56:57], v[176:177]
	v_pk_add_f32 v[50:51], v[50:51], v[178:179]
	v_pk_add_f32 v[52:53], v[52:53], v[180:181]
	v_cvt_pk_bf16_f32 v166, v62, v63
	v_cvt_pk_bf16_f32 v167, v64, v65
	v_cvt_pk_bf16_f32 v168, v58, v59
	v_cvt_pk_bf16_f32 v169, v60, v61
	v_cvt_pk_bf16_f32 v170, v54, v55
	v_cvt_pk_bf16_f32 v171, v56, v57
	v_cvt_pk_bf16_f32 v172, v50, v51
	v_cvt_pk_bf16_f32 v173, v52, v53
	v_add_u32_e32 v253, 0x40000, v252
	s_nop 1
	v_permlane16_swap_b32_e32 v166, v168
	v_permlane16_swap_b32_e32 v167, v169
	v_permlane16_swap_b32_e32 v170, v172
	v_permlane16_swap_b32_e32 v171, v173
	global_store_dwordx4 v253, v[166:169], s[14:15]
	global_store_dwordx4 v253, v[170:173], s[14:15] offset:256
	s_nop 1
	s_waitcnt vmcnt(14)
; __device__ __forceinline__ float bf_lo(unsigned u) { return __uint_as_float(u << 16); }
; __device__ __forceinline__ float bf_hi(unsigned u) { return __uint_as_float(u & 0xffff0000u); }
; __device__ __forceinline__ unsigned pk_bf16(float lo, float hi) { const f32x2 v = {lo, hi}; const bf16x2_t b = __builtin_convertvector(v, bf16x2_t); return __builtin_bit_cast(unsigned, b); }
;     __device__ __forceinline__ void operator()(const f32x4 (&acc)[2][2][4][2], const pg8::Unit& u, int wr, int wc, int fr, int fq) const {
;     ...
; #pragma unroll
;                     for (int bj = 0; bj < 2; ++bj)
; #pragma unroll
;                         for (int n = 0; n < 2; ++n) { const u32x2 w = *(const u32x2*)(XB + off + bj * 128 + n * 16); r4[bj][n] = (f32x4){bf_lo(w.x), bf_hi(w.x), bf_lo(w.y), bf_hi(w.y)}; }
;                 }
; #pragma unroll
;                 for (int bj = 0; bj < 2; ++bj)
; #pragma unroll
;                     for (int n = 0; n < 2; ++n) { const f32x4 x4 = r4[bj][n] + acc[ai][bj][m][n];
;                         q += (x4[0] * x4[0] + x4[1] * x4[1]) + (x4[2] * x4[2] + x4[3] * x4[3]);
;                         u32x2 w; w.x = pk_bf16(x4[0], x4[1]); w.y = pk_bf16(x4[2], x4[3]); *(u32x2*)(XB + off + bj * 128 + n * 16) = w; }
	v_permlane16_swap_b32_e32 v244, v246
	v_permlane16_swap_b32_e32 v245, v247
	v_permlane16_swap_b32_e32 v248, v250
	v_permlane16_swap_b32_e32 v249, v251
	v_lshlrev_b32_e32 v166, 16, v244
	v_and_b32_e32 v167, 0xffff0000, v244
	v_lshlrev_b32_e32 v168, 16, v245
	v_and_b32_e32 v169, 0xffff0000, v245
	v_lshlrev_b32_e32 v170, 16, v246
	v_and_b32_e32 v171, 0xffff0000, v246
	v_lshlrev_b32_e32 v172, 16, v247
	v_and_b32_e32 v173, 0xffff0000, v247
	v_lshlrev_b32_e32 v174, 16, v248
	v_and_b32_e32 v175, 0xffff0000, v248
	v_lshlrev_b32_e32 v176, 16, v249
	v_and_b32_e32 v177, 0xffff0000, v249
	v_lshlrev_b32_e32 v178, 16, v250
	v_and_b32_e32 v179, 0xffff0000, v250
	v_lshlrev_b32_e32 v180, 16, v251
	v_and_b32_e32 v181, 0xffff0000, v251
	v_pk_add_f32 v[46:47], v[46:47], v[166:167]
	v_pk_add_f32 v[48:49], v[48:49], v[168:169]
	v_pk_add_f32 v[42:43], v[42:43], v[170:171]
	v_pk_add_f32 v[44:45], v[44:45], v[172:173]
	v_pk_add_f32 v[38:39], v[38:39], v[174:175]
	v_pk_add_f32 v[40:41], v[40:41], v[176:177]
	v_pk_add_f32 v[34:35], v[34:35], v[178:179]
	v_pk_add_f32 v[36:37], v[36:37], v[180:181]
	v_cvt_pk_bf16_f32 v166, v46, v47
	v_cvt_pk_bf16_f32 v167, v48, v49
	v_cvt_pk_bf16_f32 v168, v42, v43
	v_cvt_pk_bf16_f32 v169, v44, v45
	v_cvt_pk_bf16_f32 v170, v38, v39
	v_cvt_pk_bf16_f32 v171, v40, v41
	v_cvt_pk_bf16_f32 v172, v34, v35
	v_cvt_pk_bf16_f32 v173, v36, v37
	v_add_u32_e32 v253, 0x48000, v252
	s_nop 1
	v_permlane16_swap_b32_e32 v166, v168
	v_permlane16_swap_b32_e32 v167, v169
	v_permlane16_swap_b32_e32 v170, v172
	v_permlane16_swap_b32_e32 v171, v173
	global_store_dwordx4 v253, v[166:169], s[14:15]
	global_store_dwordx4 v253, v[170:173], s[14:15] offset:256
	s_nop 1
	s_waitcnt vmcnt(14)
	v_permlane16_swap_b32_e32 v204, v206
	v_permlane16_swap_b32_e32 v205, v207
	v_permlane16_swap_b32_e32 v208, v210
	v_permlane16_swap_b32_e32 v209, v211
	v_lshlrev_b32_e32 v166, 16, v204
	v_and_b32_e32 v167, 0xffff0000, v204
	v_lshlrev_b32_e32 v168, 16, v205
	v_and_b32_e32 v169, 0xffff0000, v205
	v_lshlrev_b32_e32 v170, 16, v206
	v_and_b32_e32 v171, 0xffff0000, v206
	v_lshlrev_b32_e32 v172, 16, v207
	v_and_b32_e32 v173, 0xffff0000, v207
	v_lshlrev_b32_e32 v174, 16, v208
	v_and_b32_e32 v175, 0xffff0000, v208
	v_lshlrev_b32_e32 v176, 16, v209
	v_and_b32_e32 v177, 0xffff0000, v209
	v_lshlrev_b32_e32 v178, 16, v210
	v_and_b32_e32 v179, 0xffff0000, v210
	v_lshlrev_b32_e32 v180, 16, v211
	v_and_b32_e32 v181, 0xffff0000, v211
	v_pk_add_f32 v[30:31], v[30:31], v[166:167]
	v_pk_add_f32 v[32:33], v[32:33], v[168:169]
	v_pk_add_f32 v[26:27], v[26:27], v[170:171]
	v_pk_add_f32 v[28:29], v[28:29], v[172:173]
	v_pk_add_f32 v[22:23], v[22:23], v[174:175]
	v_pk_add_f32 v[24:25], v[24:25], v[176:177]
	v_pk_add_f32 v[18:19], v[18:19], v[178:179]
	v_pk_add_f32 v[20:21], v[20:21], v[180:181]
	v_cvt_pk_bf16_f32 v166, v30, v31
	v_cvt_pk_bf16_f32 v167, v32, v33
	v_cvt_pk_bf16_f32 v168, v26, v27
	v_cvt_pk_bf16_f32 v169, v28, v29
	v_cvt_pk_bf16_f32 v170, v22, v23
	v_cvt_pk_bf16_f32 v171, v24, v25
	v_cvt_pk_bf16_f32 v172, v18, v19
	v_cvt_pk_bf16_f32 v173, v20, v21
	v_add_u32_e32 v253, 0x50000, v252
	s_nop 1
	v_permlane16_swap_b32_e32 v166, v168
	v_permlane16_swap_b32_e32 v167, v169
	v_permlane16_swap_b32_e32 v170, v172
	v_permlane16_swap_b32_e32 v171, v173
	global_store_dwordx4 v253, v[166:169], s[14:15]
	global_store_dwordx4 v253, v[170:173], s[14:15] offset:256
	s_nop 1
	s_waitcnt vmcnt(12)
	v_permlane16_swap_b32_e32 v212, v214
	v_permlane16_swap_b32_e32 v213, v215
	v_permlane16_swap_b32_e32 v216, v218
	v_permlane16_swap_b32_e32 v217, v219
	v_lshlrev_b32_e32 v166, 16, v212
	v_and_b32_e32 v167, 0xffff0000, v212
	v_lshlrev_b32_e32 v168, 16, v213
	v_and_b32_e32 v169, 0xffff0000, v213
	v_lshlrev_b32_e32 v170, 16, v214
	v_and_b32_e32 v171, 0xffff0000, v214
	v_lshlrev_b32_e32 v172, 16, v215
	v_and_b32_e32 v173, 0xffff0000, v215
	v_lshlrev_b32_e32 v174, 16, v216
	v_and_b32_e32 v175, 0xffff0000, v216
	v_lshlrev_b32_e32 v176, 16, v217
	v_and_b32_e32 v177, 0xffff0000, v217
	v_lshlrev_b32_e32 v178, 16, v218
	v_and_b32_e32 v179, 0xffff0000, v218
	v_lshlrev_b32_e32 v180, 16, v219
	v_and_b32_e32 v181, 0xffff0000, v219
	v_pk_add_f32 v[14:15], v[14:15], v[166:167]
	v_pk_add_f32 v[16:17], v[16:17], v[168:169]
	v_pk_add_f32 v[10:11], v[10:11], v[170:171]
	v_pk_add_f32 v[12:13], v[12:13], v[172:173]
	v_pk_add_f32 v[6:7], v[6:7], v[174:175]
	v_pk_add_f32 v[8:9], v[8:9], v[176:177]
	v_pk_add_f32 v[2:3], v[2:3], v[178:179]
	v_pk_add_f32 v[4:5], v[4:5], v[180:181]
	v_cvt_pk_bf16_f32 v166, v14, v15
	v_cvt_pk_bf16_f32 v167, v16, v17
	v_cvt_pk_bf16_f32 v168, v10, v11
	v_cvt_pk_bf16_f32 v169, v12, v13
	v_cvt_pk_bf16_f32 v170, v6, v7
	v_cvt_pk_bf16_f32 v171, v8, v9
	v_cvt_pk_bf16_f32 v172, v2, v3
	v_cvt_pk_bf16_f32 v173, v4, v5
	v_add_u32_e32 v253, 0x58000, v252
	s_nop 1
	v_permlane16_swap_b32_e32 v166, v168
	v_permlane16_swap_b32_e32 v167, v169
	v_permlane16_swap_b32_e32 v170, v172
	v_permlane16_swap_b32_e32 v171, v173
	global_store_dwordx4 v253, v[166:169], s[14:15]
	global_store_dwordx4 v253, v[170:173], s[14:15] offset:256
	s_nop 1
	v_mul_f32_e32 v166, v126, v126
	v_mul_f32_e32 v167, v122, v122
	v_mul_f32_e32 v168, v118, v118
	v_mul_f32_e32 v169, v114, v114
	v_fmac_f32_e32 v166, v127, v127
	v_fmac_f32_e32 v167, v123, v123
	v_fmac_f32_e32 v168, v119, v119
	v_fmac_f32_e32 v169, v115, v115
	v_fmac_f32_e32 v166, v128, v128
	v_fmac_f32_e32 v167, v124, v124
	v_fmac_f32_e32 v168, v120, v120
	v_fmac_f32_e32 v169, v116, v116
	v_fmac_f32_e32 v166, v129, v129
	v_fmac_f32_e32 v167, v125, v125
	v_fmac_f32_e32 v168, v121, v121
	v_fmac_f32_e32 v169, v117, v117
	v_add_f32_e32 v166, v166, v167
	v_add_f32_e32 v168, v168, v169
; __device__ __forceinline__ unsigned pk_bf16(float lo, float hi) { const f32x2 v = {lo, hi}; const bf16x2_t b = __builtin_convertvector(v, bf16x2_t); return __builtin_bit_cast(unsigned, b); }
;     __device__ __forceinline__ void operator()(const f32x4 (&acc)[2][2][4][2], const pg8::Unit& u, int wr, int wc, int fr, int fq) const {
;     ...
;                     for (int n = 0; n < 2; ++n) { const f32x4 x4 = r4[bj][n] + acc[ai][bj][m][n];
;                         q += (x4[0] * x4[0] + x4[1] * x4[1]) + (x4[2] * x4[2] + x4[3] * x4[3]);
;                         u32x2 w; w.x = pk_bf16(x4[0], x4[1]); w.y = pk_bf16(x4[2], x4[3]); *(u32x2*)(XB + off + bj * 128 + n * 16) = w; }
;                 q += __shfl_xor(q, 16); q += __shfl_xor(q, 32);
;                 if (fq == 0) ssq[(size_t)row * 16 + u.pn * 4 + wc] = q;
	v_add_f32_e32 v178, v166, v168
	v_mov_b32_e32 v179, v178
	s_nop 0
	s_nop 0
	v_permlane32_swap_b32_e32 v179, v178
	v_add_f32_e32 v178, v178, v179
	v_mov_b32_e32 v179, v178
	s_nop 1
	v_permlane16_swap_b32_e32 v179, v178
	v_add_f32_e32 v178, v178, v179
	s_and_saveexec_b64 s[30:31], s[8:9]
	global_store_dword v189, v178, s[16:17]
	s_or_b64 exec, exec, s[30:31]
	v_mul_f32_e32 v170, v110, v110
	v_mul_f32_e32 v171, v106, v106
	v_mul_f32_e32 v172, v102, v102
	v_mul_f32_e32 v173, v98, v98
	v_fmac_f32_e32 v170, v111, v111
	v_fmac_f32_e32 v171, v107, v107
	v_fmac_f32_e32 v172, v103, v103
	v_fmac_f32_e32 v173, v99, v99
	v_fmac_f32_e32 v170, v112, v112
	v_fmac_f32_e32 v171, v108, v108
	v_fmac_f32_e32 v172, v104, v104
	v_fmac_f32_e32 v173, v100, v100
	v_fmac_f32_e32 v170, v113, v113
	v_fmac_f32_e32 v171, v109, v109
	v_fmac_f32_e32 v172, v105, v105
	v_fmac_f32_e32 v173, v101, v101
	v_add_f32_e32 v170, v170, v171
	v_add_f32_e32 v172, v172, v173
	v_add_f32_e32 v180, v170, v172
	v_mov_b32_e32 v181, v180
	s_nop 0
	s_nop 0
	v_permlane32_swap_b32_e32 v181, v180
	v_add_f32_e32 v180, v180, v181
	v_mov_b32_e32 v181, v180
	s_nop 1
	v_permlane16_swap_b32_e32 v181, v180
	v_add_f32_e32 v180, v180, v181
	s_and_saveexec_b64 s[30:31], s[8:9]
	global_store_dword v189, v180, s[16:17] offset:1024
	s_or_b64 exec, exec, s[30:31]
	v_mul_f32_e32 v166, v94, v94
	v_mul_f32_e32 v167, v90, v90
	v_mul_f32_e32 v168, v86, v86
	v_mul_f32_e32 v169, v82, v82
	v_fmac_f32_e32 v166, v95, v95
	v_fmac_f32_e32 v167, v91, v91
	v_fmac_f32_e32 v168, v87, v87
	v_fmac_f32_e32 v169, v83, v83
	v_fmac_f32_e32 v166, v96, v96
	v_fmac_f32_e32 v167, v92, v92
	v_fmac_f32_e32 v168, v88, v88
	v_fmac_f32_e32 v169, v84, v84
	v_fmac_f32_e32 v166, v97, v97
	v_fmac_f32_e32 v167, v93, v93
	v_fmac_f32_e32 v168, v89, v89
	v_fmac_f32_e32 v169, v85, v85
	v_add_f32_e32 v166, v166, v167
	v_add_f32_e32 v168, v168, v169
	v_add_f32_e32 v178, v166, v168
	v_mov_b32_e32 v179, v178
	s_nop 0
	s_nop 0
	v_permlane32_swap_b32_e32 v179, v178
	v_add_f32_e32 v178, v178, v179
	v_mov_b32_e32 v179, v178
	s_nop 1
	v_permlane16_swap_b32_e32 v179, v178
	v_add_f32_e32 v178, v178, v179
	s_and_saveexec_b64 s[30:31], s[8:9]
	global_store_dword v189, v178, s[16:17] offset:2048
	s_or_b64 exec, exec, s[30:31]
	v_mul_f32_e32 v170, v78, v78
	v_mul_f32_e32 v171, v74, v74
	v_mul_f32_e32 v172, v70, v70
	v_mul_f32_e32 v173, v66, v66
	v_fmac_f32_e32 v170, v79, v79
	v_fmac_f32_e32 v171, v75, v75
	v_fmac_f32_e32 v172, v71, v71
	v_fmac_f32_e32 v173, v67, v67
	v_fmac_f32_e32 v170, v80, v80
	v_fmac_f32_e32 v171, v76, v76
	v_fmac_f32_e32 v172, v72, v72
	v_fmac_f32_e32 v173, v68, v68
	v_fmac_f32_e32 v170, v81, v81
	v_fmac_f32_e32 v171, v77, v77
	v_fmac_f32_e32 v172, v73, v73
	v_fmac_f32_e32 v173, v69, v69
	v_add_f32_e32 v170, v170, v171
	v_add_f32_e32 v172, v172, v173
	v_add_f32_e32 v180, v170, v172
	v_mov_b32_e32 v181, v180
	s_nop 0
	s_nop 0
	v_permlane32_swap_b32_e32 v181, v180
	v_add_f32_e32 v180, v180, v181
	v_mov_b32_e32 v181, v180
	s_nop 1
	v_permlane16_swap_b32_e32 v181, v180
	v_add_f32_e32 v180, v180, v181
	s_and_saveexec_b64 s[30:31], s[8:9]
	global_store_dword v189, v180, s[16:17] offset:3072
	s_or_b64 exec, exec, s[30:31]
	v_mul_f32_e32 v166, v62, v62
	v_mul_f32_e32 v167, v58, v58
	v_mul_f32_e32 v168, v54, v54
	v_mul_f32_e32 v169, v50, v50
	v_fmac_f32_e32 v166, v63, v63
	v_fmac_f32_e32 v167, v59, v59
	v_fmac_f32_e32 v168, v55, v55
	v_fmac_f32_e32 v169, v51, v51
	v_fmac_f32_e32 v166, v64, v64
	v_fmac_f32_e32 v167, v60, v60
	v_fmac_f32_e32 v168, v56, v56
	v_fmac_f32_e32 v169, v52, v52
	v_fmac_f32_e32 v166, v65, v65
	v_fmac_f32_e32 v167, v61, v61
	v_fmac_f32_e32 v168, v57, v57
	v_fmac_f32_e32 v169, v53, v53
	v_add_f32_e32 v166, v166, v167
	v_add_f32_e32 v168, v168, v169
	v_add_f32_e32 v178, v166, v168
	v_mov_b32_e32 v179, v178
	v_add_u32_e32 v189, 0x2000, v189
	s_nop 0
	v_permlane32_swap_b32_e32 v179, v178
	v_add_f32_e32 v178, v178, v179
	v_mov_b32_e32 v179, v178
	s_nop 1
	v_permlane16_swap_b32_e32 v179, v178
	v_add_f32_e32 v178, v178, v179
	s_and_saveexec_b64 s[30:31], s[8:9]
	global_store_dword v189, v178, s[16:17]
	s_or_b64 exec, exec, s[30:31]
	v_mul_f32_e32 v170, v46, v46
	v_mul_f32_e32 v171, v42, v42
	v_mul_f32_e32 v172, v38, v38
	v_mul_f32_e32 v173, v34, v34
	v_fmac_f32_e32 v170, v47, v47
	v_fmac_f32_e32 v171, v43, v43
	v_fmac_f32_e32 v172, v39, v39
	v_fmac_f32_e32 v173, v35, v35
	v_fmac_f32_e32 v170, v48, v48
	v_fmac_f32_e32 v171, v44, v44
	v_fmac_f32_e32 v172, v40, v40
	v_fmac_f32_e32 v173, v36, v36
	v_fmac_f32_e32 v170, v49, v49
	v_fmac_f32_e32 v171, v45, v45
	v_fmac_f32_e32 v172, v41, v41
	v_fmac_f32_e32 v173, v37, v37
	v_add_f32_e32 v170, v170, v171
	v_add_f32_e32 v172, v172, v173
	v_add_f32_e32 v180, v170, v172
	v_mov_b32_e32 v181, v180
	s_nop 0
	s_nop 0
	v_permlane32_swap_b32_e32 v181, v180
	v_add_f32_e32 v180, v180, v181
	v_mov_b32_e32 v181, v180
	s_nop 1
	v_permlane16_swap_b32_e32 v181, v180
	v_add_f32_e32 v180, v180, v181
	s_and_saveexec_b64 s[30:31], s[8:9]
	global_store_dword v189, v180, s[16:17] offset:1024
	s_or_b64 exec, exec, s[30:31]
	v_mul_f32_e32 v166, v30, v30
	v_mul_f32_e32 v167, v26, v26
	v_mul_f32_e32 v168, v22, v22
	v_mul_f32_e32 v169, v18, v18
	v_fmac_f32_e32 v166, v31, v31
	v_fmac_f32_e32 v167, v27, v27
	v_fmac_f32_e32 v168, v23, v23
	v_fmac_f32_e32 v169, v19, v19
	v_fmac_f32_e32 v166, v32, v32
	v_fmac_f32_e32 v167, v28, v28
	v_fmac_f32_e32 v168, v24, v24
	v_fmac_f32_e32 v169, v20, v20
	v_fmac_f32_e32 v166, v33, v33
	v_fmac_f32_e32 v167, v29, v29
	v_fmac_f32_e32 v168, v25, v25
	v_fmac_f32_e32 v169, v21, v21
	v_add_f32_e32 v166, v166, v167
	v_add_f32_e32 v168, v168, v169
	v_add_f32_e32 v178, v166, v168
	v_mov_b32_e32 v179, v178
	s_nop 0
	s_nop 0
	v_permlane32_swap_b32_e32 v179, v178
	v_add_f32_e32 v178, v178, v179
	v_mov_b32_e32 v179, v178
	s_nop 1
	v_permlane16_swap_b32_e32 v179, v178
	v_add_f32_e32 v178, v178, v179
	s_and_saveexec_b64 s[30:31], s[8:9]
	global_store_dword v189, v178, s[16:17] offset:2048
	s_or_b64 exec, exec, s[30:31]
	v_mul_f32_e32 v170, v14, v14
	v_mul_f32_e32 v171, v10, v10
	v_mul_f32_e32 v172, v6, v6
	v_mul_f32_e32 v173, v2, v2
	v_fmac_f32_e32 v170, v15, v15
	v_fmac_f32_e32 v171, v11, v11
	v_fmac_f32_e32 v172, v7, v7
	v_fmac_f32_e32 v173, v3, v3
	v_fmac_f32_e32 v170, v16, v16
	v_fmac_f32_e32 v171, v12, v12
	v_fmac_f32_e32 v172, v8, v8
	v_fmac_f32_e32 v173, v4, v4
	v_fmac_f32_e32 v170, v17, v17
	v_fmac_f32_e32 v171, v13, v13
	v_fmac_f32_e32 v172, v9, v9
	v_fmac_f32_e32 v173, v5, v5
	v_add_f32_e32 v170, v170, v171
	v_add_f32_e32 v172, v172, v173
	v_add_f32_e32 v180, v170, v172
	v_mov_b32_e32 v181, v180
	s_nop 0
	s_nop 0
	v_permlane32_swap_b32_e32 v181, v180
	v_add_f32_e32 v180, v180, v181
	v_mov_b32_e32 v181, v180
	s_nop 1
	v_permlane16_swap_b32_e32 v181, v180
	v_add_f32_e32 v180, v180, v181
	s_and_saveexec_b64 s[30:31], s[8:9]
	global_store_dword v189, v180, s[16:17] offset:3072
	s_or_b64 exec, exec, s[30:31]

; __device__ __forceinline__ float bf_lo(unsigned u) { return __uint_as_float(u << 16); }
; __device__ __forceinline__ float bf_hi(unsigned u) { return __uint_as_float(u & 0xffff0000u); }
; __device__ __forceinline__ unsigned pk_bf16(float lo, float hi) { const f32x2 v = {lo, hi}; const bf16x2_t b = __builtin_convertvector(v, bf16x2_t); return __builtin_bit_cast(unsigned, b); }
;     __device__ __forceinline__ void operator()(const f32x4 (&acc)[2][2][4][2], const pg8::Unit& u, int wr, int wc, int fr, int fq) const {
;     ...
;         const int row0 = u.pm * 256 + wr * 64 + fr, col0 = u.pn * 256 + wc * 32 + 4 * fq;
;         const bool rf32 = (rp != nullptr) && (u.pm < MP / 256);
; #pragma unroll
;         for (int ai = 0; ai < 2; ++ai)
; #pragma unroll
;             for (int m = 0; m < 4; ++m) {
;                 const int row = row0 + ai * 128 + m * 16; const size_t off = (size_t)row * DM + col0; float q = 0.f;
;                 f32x4 r4[2][2];
;                 if (rf32) {
; #pragma unroll
;                     for (int bj = 0; bj < 2; ++bj)
; #pragma unroll
;                         for (int n = 0; n < 2; ++n) r4[bj][n] = *(const f32x4*)(rp + off + bj * 128 + n * 16);
;                 } else {
; #pragma unroll
;                     for (int bj = 0; bj < 2; ++bj)
; #pragma unroll
;                         for (int n = 0; n < 2; ++n) { const u32x2 w = *(const u32x2*)(XB + off + bj * 128 + n * 16); r4[bj][n] = (f32x4){bf_lo(w.x), bf_hi(w.x), bf_lo(w.y), bf_hi(w.y)}; }
;                 }
; #pragma unroll
;                 for (int bj = 0; bj < 2; ++bj)
; #pragma unroll
;                     for (int n = 0; n < 2; ++n) { const f32x4 x4 = r4[bj][n] + acc[ai][bj][m][n];
;                         q += (x4[0] * x4[0] + x4[1] * x4[1]) + (x4[2] * x4[2] + x4[3] * x4[3]);
;                         u32x2 w; w.x = pk_bf16(x4[0], x4[1]); w.y = pk_bf16(x4[2], x4[3]); *(u32x2*)(XB + off + bj * 128 + n * 16) = w; }
.LBB0_1893:
	s_lshl_b32 s4, s47, 8
	v_mov_b32_e32 v158, v1
	s_add_i32 s4, s4, s40
	s_lshl_b32 s22, s46, 2
	v_add_u32_e32 v160, s4, v158
	v_ashrrev_i32_e32 v161, 31, v160
	v_lshl_or_b32 v158, s46, 8, v163
	v_lshlrev_b64 v[166:167], 11, v[160:161]
	v_ashrrev_i32_e32 v159, 31, v158
	v_lshl_add_u64 v[166:167], s[14:15], 0, v[166:167]
	v_lshl_add_u64 v[166:167], v[158:159], 1, v[166:167]
	s_ashr_i32 s23, s22, 31
	v_lshlrev_b32_e32 v252, 11, v160
	v_lshl_add_u32 v252, v158, 1, v252
	v_bfe_u32 v253, v190, 4, 1
	v_mul_u32_u24_e32 v253, 24, v253
	v_add_u32_e32 v252, v252, v253
	s_lshl_b32 s88, s39, 2
	v_lshl_add_u32 v189, v160, 6, s88
	v_lshl_add_u32 v189, s22, 2, v189
	global_load_dwordx4 v[204:207], v252, s[14:15]
	global_load_dwordx4 v[208:211], v252, s[14:15] offset:256
	v_add_u32_e32 v253, 0x8000, v252
	global_load_dwordx4 v[212:215], v253, s[14:15]
	global_load_dwordx4 v[216:219], v253, s[14:15] offset:256
	v_add_u32_e32 v253, 0x10000, v252
	global_load_dwordx4 v[220:223], v253, s[14:15]
	global_load_dwordx4 v[224:227], v253, s[14:15] offset:256
	v_add_u32_e32 v253, 0x18000, v252
	global_load_dwordx4 v[228:231], v253, s[14:15]
	global_load_dwordx4 v[232:235], v253, s[14:15] offset:256
	v_add_u32_e32 v253, 0x40000, v252
	global_load_dwordx4 v[236:239], v253, s[14:15]
	global_load_dwordx4 v[240:243], v253, s[14:15] offset:256
	v_add_u32_e32 v253, 0x48000, v252
	global_load_dwordx4 v[244:247], v253, s[14:15]
	global_load_dwordx4 v[248:251], v253, s[14:15] offset:256
	s_waitcnt vmcnt(10)
	v_permlane16_swap_b32_e32 v204, v206
	v_permlane16_swap_b32_e32 v205, v207
	v_permlane16_swap_b32_e32 v208, v210
	v_permlane16_swap_b32_e32 v209, v211
	v_lshlrev_b32_e32 v166, 16, v204
	v_and_b32_e32 v167, 0xffff0000, v204
	v_lshlrev_b32_e32 v168, 16, v205
	v_and_b32_e32 v169, 0xffff0000, v205
	v_lshlrev_b32_e32 v170, 16, v206
	v_and_b32_e32 v171, 0xffff0000, v206
	v_lshlrev_b32_e32 v172, 16, v207
	v_and_b32_e32 v173, 0xffff0000, v207
	v_lshlrev_b32_e32 v174, 16, v208
	v_and_b32_e32 v175, 0xffff0000, v208
	v_lshlrev_b32_e32 v176, 16, v209
	v_and_b32_e32 v177, 0xffff0000, v209
	v_lshlrev_b32_e32 v178, 16, v210
	v_and_b32_e32 v179, 0xffff0000, v210
	v_lshlrev_b32_e32 v180, 16, v211
	v_and_b32_e32 v181, 0xffff0000, v211
	v_pk_add_f32 v[126:127], v[126:127], v[166:167]
	v_pk_add_f32 v[128:129], v[128:129], v[168:169]
	v_pk_add_f32 v[122:123], v[122:123], v[170:171]
	v_pk_add_f32 v[124:125], v[124:125], v[172:173]
	v_pk_add_f32 v[118:119], v[118:119], v[174:175]
	v_pk_add_f32 v[120:121], v[120:121], v[176:177]
	v_pk_add_f32 v[114:115], v[114:115], v[178:179]
	v_pk_add_f32 v[116:117], v[116:117], v[180:181]
	v_add_u32_e32 v253, 0x50000, v252
	global_load_dwordx4 v[204:207], v253, s[14:15]
	global_load_dwordx4 v[208:211], v253, s[14:15] offset:256
	v_cvt_pk_bf16_f32 v166, v126, v127
	v_cvt_pk_bf16_f32 v167, v128, v129
	v_cvt_pk_bf16_f32 v168, v122, v123
	v_cvt_pk_bf16_f32 v169, v124, v125
	v_cvt_pk_bf16_f32 v170, v118, v119
	v_cvt_pk_bf16_f32 v171, v120, v121
	v_cvt_pk_bf16_f32 v172, v114, v115
	v_cvt_pk_bf16_f32 v173, v116, v117
	s_nop 1
	v_permlane16_swap_b32_e32 v166, v168
	v_permlane16_swap_b32_e32 v167, v169
	v_permlane16_swap_b32_e32 v170, v172
	v_permlane16_swap_b32_e32 v171, v173
	global_store_dwordx4 v252, v[166:169], s[14:15]
	global_store_dwordx4 v252, v[170:173], s[14:15] offset:256
	s_nop 1
	s_waitcnt vmcnt(12)
	v_permlane16_swap_b32_e32 v212, v214
	v_permlane16_swap_b32_e32 v213, v215
	v_permlane16_swap_b32_e32 v216, v218
	v_permlane16_swap_b32_e32 v217, v219
	v_lshlrev_b32_e32 v166, 16, v212
	v_and_b32_e32 v167, 0xffff0000, v212
	v_lshlrev_b32_e32 v168, 16, v213
	v_and_b32_e32 v169, 0xffff0000, v213
	v_lshlrev_b32_e32 v170, 16, v214
	v_and_b32_e32 v171, 0xffff0000, v214
	v_lshlrev_b32_e32 v172, 16, v215
	v_and_b32_e32 v173, 0xffff0000, v215
	v_lshlrev_b32_e32 v174, 16, v216
	v_and_b32_e32 v175, 0xffff0000, v216
	v_lshlrev_b32_e32 v176, 16, v217
	v_and_b32_e32 v177, 0xffff0000, v217
	v_lshlrev_b32_e32 v178, 16, v218
	v_and_b32_e32 v179, 0xffff0000, v218
	v_lshlrev_b32_e32 v180, 16, v219
	v_and_b32_e32 v181, 0xffff0000, v219
	v_pk_add_f32 v[110:111], v[110:111], v[166:167]
	v_pk_add_f32 v[112:113], v[112:113], v[168:169]
	v_pk_add_f32 v[106:107], v[106:107], v[170:171]
	v_pk_add_f32 v[108:109], v[108:109], v[172:173]
	v_pk_add_f32 v[102:103], v[102:103], v[174:175]
	v_pk_add_f32 v[104:105], v[104:105], v[176:177]
	v_pk_add_f32 v[98:99], v[98:99], v[178:179]
	v_pk_add_f32 v[100:101], v[100:101], v[180:181]
	v_add_u32_e32 v253, 0x58000, v252
	global_load_dwordx4 v[212:215], v253, s[14:15]
	global_load_dwordx4 v[216:219], v253, s[14:15] offset:256
	v_cvt_pk_bf16_f32 v166, v110, v111
	v_cvt_pk_bf16_f32 v167, v112, v113
	v_cvt_pk_bf16_f32 v168, v106, v107
	v_cvt_pk_bf16_f32 v169, v108, v109
	v_cvt_pk_bf16_f32 v170, v102, v103
	v_cvt_pk_bf16_f32 v171, v104, v105
	v_cvt_pk_bf16_f32 v172, v98, v99
	v_cvt_pk_bf16_f32 v173, v100, v101
	v_add_u32_e32 v253, 0x8000, v252
	s_nop 1
	v_permlane16_swap_b32_e32 v166, v168
	v_permlane16_swap_b32_e32 v167, v169
	v_permlane16_swap_b32_e32 v170, v172
	v_permlane16_swap_b32_e32 v171, v173
	global_store_dwordx4 v253, v[166:169], s[14:15]
	global_store_dwordx4 v253, v[170:173], s[14:15] offset:256
	s_nop 1
	s_waitcnt vmcnt(14)
; __device__ __forceinline__ float bf_lo(unsigned u) { return __uint_as_float(u << 16); }
; __device__ __forceinline__ float bf_hi(unsigned u) { return __uint_as_float(u & 0xffff0000u); }
; __device__ __forceinline__ unsigned pk_bf16(float lo, float hi) { const f32x2 v = {lo, hi}; const bf16x2_t b = __builtin_convertvector(v, bf16x2_t); return __builtin_bit_cast(unsigned, b); }
;     __device__ __forceinline__ void operator()(const f32x4 (&acc)[2][2][4][2], const pg8::Unit& u, int wr, int wc, int fr, int fq) const {
;     ...
; #pragma unroll
;                     for (int bj = 0; bj < 2; ++bj)
; #pragma unroll
;                         for (int n = 0; n < 2; ++n) { const u32x2 w = *(const u32x2*)(XB + off + bj * 128 + n * 16); r4[bj][n] = (f32x4){bf_lo(w.x), bf_hi(w.x), bf_lo(w.y), bf_hi(w.y)}; }
;                 }
; #pragma unroll
;                 for (int bj = 0; bj < 2; ++bj)
; #pragma unroll
;                     for (int n = 0; n < 2; ++n) { const f32x4 x4 = r4[bj][n] + acc[ai][bj][m][n];
;                         q += (x4[0] * x4[0] + x4[1] * x4[1]) + (x4[2] * x4[2] + x4[3] * x4[3]);
;                         u32x2 w; w.x = pk_bf16(x4[0], x4[1]); w.y = pk_bf16(x4[2], x4[3]); *(u32x2*)(XB + off + bj * 128 + n * 16) = w; }
	v_permlane16_swap_b32_e32 v220, v222
	v_permlane16_swap_b32_e32 v221, v223
	v_permlane16_swap_b32_e32 v224, v226
	v_permlane16_swap_b32_e32 v225, v227
	v_lshlrev_b32_e32 v166, 16, v220
	v_and_b32_e32 v167, 0xffff0000, v220
	v_lshlrev_b32_e32 v168, 16, v221
	v_and_b32_e32 v169, 0xffff0000, v221
	v_lshlrev_b32_e32 v170, 16, v222
	v_and_b32_e32 v171, 0xffff0000, v222
	v_lshlrev_b32_e32 v172, 16, v223
	v_and_b32_e32 v173, 0xffff0000, v223
	v_lshlrev_b32_e32 v174, 16, v224
	v_and_b32_e32 v175, 0xffff0000, v224
	v_lshlrev_b32_e32 v176, 16, v225
	v_and_b32_e32 v177, 0xffff0000, v225
	v_lshlrev_b32_e32 v178, 16, v226
	v_and_b32_e32 v179, 0xffff0000, v226
	v_lshlrev_b32_e32 v180, 16, v227
	v_and_b32_e32 v181, 0xffff0000, v227
	v_pk_add_f32 v[94:95], v[94:95], v[166:167]
	v_pk_add_f32 v[96:97], v[96:97], v[168:169]
	v_pk_add_f32 v[90:91], v[90:91], v[170:171]
	v_pk_add_f32 v[92:93], v[92:93], v[172:173]
	v_pk_add_f32 v[86:87], v[86:87], v[174:175]
	v_pk_add_f32 v[88:89], v[88:89], v[176:177]
	v_pk_add_f32 v[82:83], v[82:83], v[178:179]
	v_pk_add_f32 v[84:85], v[84:85], v[180:181]
	v_cvt_pk_bf16_f32 v166, v94, v95
	v_cvt_pk_bf16_f32 v167, v96, v97
	v_cvt_pk_bf16_f32 v168, v90, v91
	v_cvt_pk_bf16_f32 v169, v92, v93
	v_cvt_pk_bf16_f32 v170, v86, v87
	v_cvt_pk_bf16_f32 v171, v88, v89
	v_cvt_pk_bf16_f32 v172, v82, v83
	v_cvt_pk_bf16_f32 v173, v84, v85
	v_add_u32_e32 v253, 0x10000, v252
	s_nop 1
	v_permlane16_swap_b32_e32 v166, v168
	v_permlane16_swap_b32_e32 v167, v169
	v_permlane16_swap_b32_e32 v170, v172
	v_permlane16_swap_b32_e32 v171, v173
	global_store_dwordx4 v253, v[166:169], s[14:15]
	global_store_dwordx4 v253, v[170:173], s[14:15] offset:256
	s_nop 1
	s_waitcnt vmcnt(14)
	v_permlane16_swap_b32_e32 v228, v230
	v_permlane16_swap_b32_e32 v229, v231
	v_permlane16_swap_b32_e32 v232, v234
	v_permlane16_swap_b32_e32 v233, v235
	v_lshlrev_b32_e32 v166, 16, v228
	v_and_b32_e32 v167, 0xffff0000, v228
	v_lshlrev_b32_e32 v168, 16, v229
	v_and_b32_e32 v169, 0xffff0000, v229
	v_lshlrev_b32_e32 v170, 16, v230
	v_and_b32_e32 v171, 0xffff0000, v230
	v_lshlrev_b32_e32 v172, 16, v231
	v_and_b32_e32 v173, 0xffff0000, v231
	v_lshlrev_b32_e32 v174, 16, v232
	v_and_b32_e32 v175, 0xffff0000, v232
	v_lshlrev_b32_e32 v176, 16, v233
	v_and_b32_e32 v177, 0xffff0000, v233
	v_lshlrev_b32_e32 v178, 16, v234
	v_and_b32_e32 v179, 0xffff0000, v234
	v_lshlrev_b32_e32 v180, 16, v235
	v_and_b32_e32 v181, 0xffff0000, v235
	v_pk_add_f32 v[78:79], v[78:79], v[166:167]
	v_pk_add_f32 v[80:81], v[80:81], v[168:169]
	v_pk_add_f32 v[74:75], v[74:75], v[170:171]
	v_pk_add_f32 v[76:77], v[76:77], v[172:173]
	v_pk_add_f32 v[70:71], v[70:71], v[174:175]
	v_pk_add_f32 v[72:73], v[72:73], v[176:177]
	v_pk_add_f32 v[66:67], v[66:67], v[178:179]
	v_pk_add_f32 v[68:69], v[68:69], v[180:181]
	v_cvt_pk_bf16_f32 v166, v78, v79
	v_cvt_pk_bf16_f32 v167, v80, v81
	v_cvt_pk_bf16_f32 v168, v74, v75
	v_cvt_pk_bf16_f32 v169, v76, v77
	v_cvt_pk_bf16_f32 v170, v70, v71
	v_cvt_pk_bf16_f32 v171, v72, v73
	v_cvt_pk_bf16_f32 v172, v66, v67
	v_cvt_pk_bf16_f32 v173, v68, v69
	v_add_u32_e32 v253, 0x18000, v252
	s_nop 1
	v_permlane16_swap_b32_e32 v166, v168
	v_permlane16_swap_b32_e32 v167, v169
	v_permlane16_swap_b32_e32 v170, v172
	v_permlane16_swap_b32_e32 v171, v173
	global_store_dwordx4 v253, v[166:169], s[14:15]
	global_store_dwordx4 v253, v[170:173], s[14:15] offset:256
	s_nop 1
	s_waitcnt vmcnt(14)
	v_permlane16_swap_b32_e32 v236, v238
	v_permlane16_swap_b32_e32 v237, v239
	v_permlane16_swap_b32_e32 v240, v242
	v_permlane16_swap_b32_e32 v241, v243
	v_lshlrev_b32_e32 v166, 16, v236
	v_and_b32_e32 v167, 0xffff0000, v236
	v_lshlrev_b32_e32 v168, 16, v237
	v_and_b32_e32 v169, 0xffff0000, v237
	v_lshlrev_b32_e32 v170, 16, v238
	v_and_b32_e32 v171, 0xffff0000, v238
	v_lshlrev_b32_e32 v172, 16, v239
	v_and_b32_e32 v173, 0xffff0000, v239
	v_lshlrev_b32_e32 v174, 16, v240
	v_and_b32_e32 v175, 0xffff0000, v240
	v_lshlrev_b32_e32 v176, 16, v241
	v_and_b32_e32 v177, 0xffff0000, v241
	v_lshlrev_b32_e32 v178, 16, v242
	v_and_b32_e32 v179, 0xffff0000, v242
	v_lshlrev_b32_e32 v180, 16, v243
	v_and_b32_e32 v181, 0xffff0000, v243
	v_pk_add_f32 v[62:63], v[62:63], v[166:167]
	v_pk_add_f32 v[64:65], v[64:65], v[168:169]
	v_pk_add_f32 v[58:59], v[58:59], v[170:171]
	v_pk_add_f32 v[60:61], v[60:61], v[172:173]
	v_pk_add_f32 v[54:55], v[54:55], v[174:175]
	v_pk_add_f32 v[56:57], v[56:57], v[176:177]
	v_pk_add_f32 v[50:51], v[50:51], v[178:179]
	v_pk_add_f32 v[52:53], v[52:53], v[180:181]
	v_cvt_pk_bf16_f32 v166, v62, v63
	v_cvt_pk_bf16_f32 v167, v64, v65
	v_cvt_pk_bf16_f32 v168, v58, v59
	v_cvt_pk_bf16_f32 v169, v60, v61
	v_cvt_pk_bf16_f32 v170, v54, v55
	v_cvt_pk_bf16_f32 v171, v56, v57
	v_cvt_pk_bf16_f32 v172, v50, v51
	v_cvt_pk_bf16_f32 v173, v52, v53
	v_add_u32_e32 v253, 0x40000, v252
	s_nop 1
	v_permlane16_swap_b32_e32 v166, v168
	v_permlane16_swap_b32_e32 v167, v169
	v_permlane16_swap_b32_e32 v170, v172
	v_permlane16_swap_b32_e32 v171, v173
	global_store_dwordx4 v253, v[166:169], s[14:15]
	global_store_dwordx4 v253, v[170:173], s[14:15] offset:256
	s_nop 1
	s_waitcnt vmcnt(14)
; __device__ __forceinline__ float bf_lo(unsigned u) { return __uint_as_float(u << 16); }
; __device__ __forceinline__ float bf_hi(unsigned u) { return __uint_as_float(u & 0xffff0000u); }
; __device__ __forceinline__ unsigned pk_bf16(float lo, float hi) { const f32x2 v = {lo, hi}; const bf16x2_t b = __builtin_convertvector(v, bf16x2_t); return __builtin_bit_cast(unsigned, b); }
;     __device__ __forceinline__ void operator()(const f32x4 (&acc)[2][2][4][2], const pg8::Unit& u, int wr, int wc, int fr, int fq) const {
;     ...
; #pragma unroll
;                     for (int bj = 0; bj < 2; ++bj)
; #pragma unroll
;                         for (int n = 0; n < 2; ++n) { const u32x2 w = *(const u32x2*)(XB + off + bj * 128 + n * 16); r4[bj][n] = (f32x4){bf_lo(w.x), bf_hi(w.x), bf_lo(w.y), bf_hi(w.y)}; }
;                 }
; #pragma unroll
;                 for (int bj = 0; bj < 2; ++bj)
; #pragma unroll
;                     for (int n = 0; n < 2; ++n) { const f32x4 x4 = r4[bj][n] + acc[ai][bj][m][n];
;                         q += (x4[0] * x4[0] + x4[1] * x4[1]) + (x4[2] * x4[2] + x4[3] * x4[3]);
;                         u32x2 w; w.x = pk_bf16(x4[0], x4[1]); w.y = pk_bf16(x4[2], x4[3]); *(u32x2*)(XB + off + bj * 128 + n * 16) = w; }
	v_permlane16_swap_b32_e32 v244, v246
	v_permlane16_swap_b32_e32 v245, v247
	v_permlane16_swap_b32_e32 v248, v250
	v_permlane16_swap_b32_e32 v249, v251
	v_lshlrev_b32_e32 v166, 16, v244
	v_and_b32_e32 v167, 0xffff0000, v244
	v_lshlrev_b32_e32 v168, 16, v245
	v_and_b32_e32 v169, 0xffff0000, v245
	v_lshlrev_b32_e32 v170, 16, v246
	v_and_b32_e32 v171, 0xffff0000, v246
	v_lshlrev_b32_e32 v172, 16, v247
	v_and_b32_e32 v173, 0xffff0000, v247
	v_lshlrev_b32_e32 v174, 16, v248
	v_and_b32_e32 v175, 0xffff0000, v248
	v_lshlrev_b32_e32 v176, 16, v249
	v_and_b32_e32 v177, 0xffff0000, v249
	v_lshlrev_b32_e32 v178, 16, v250
	v_and_b32_e32 v179, 0xffff0000, v250
	v_lshlrev_b32_e32 v180, 16, v251
	v_and_b32_e32 v181, 0xffff0000, v251
	v_pk_add_f32 v[46:47], v[46:47], v[166:167]
	v_pk_add_f32 v[48:49], v[48:49], v[168:169]
	v_pk_add_f32 v[42:43], v[42:43], v[170:171]
	v_pk_add_f32 v[44:45], v[44:45], v[172:173]
	v_pk_add_f32 v[38:39], v[38:39], v[174:175]
	v_pk_add_f32 v[40:41], v[40:41], v[176:177]
	v_pk_add_f32 v[34:35], v[34:35], v[178:179]
	v_pk_add_f32 v[36:37], v[36:37], v[180:181]
	v_cvt_pk_bf16_f32 v166, v46, v47
	v_cvt_pk_bf16_f32 v167, v48, v49
	v_cvt_pk_bf16_f32 v168, v42, v43
	v_cvt_pk_bf16_f32 v169, v44, v45
	v_cvt_pk_bf16_f32 v170, v38, v39
	v_cvt_pk_bf16_f32 v171, v40, v41
	v_cvt_pk_bf16_f32 v172, v34, v35
	v_cvt_pk_bf16_f32 v173, v36, v37
	v_add_u32_e32 v253, 0x48000, v252
	s_nop 1
	v_permlane16_swap_b32_e32 v166, v168
	v_permlane16_swap_b32_e32 v167, v169
	v_permlane16_swap_b32_e32 v170, v172
	v_permlane16_swap_b32_e32 v171, v173
	global_store_dwordx4 v253, v[166:169], s[14:15]
	global_store_dwordx4 v253, v[170:173], s[14:15] offset:256
	s_nop 1
	s_waitcnt vmcnt(14)
	v_permlane16_swap_b32_e32 v204, v206
	v_permlane16_swap_b32_e32 v205, v207
	v_permlane16_swap_b32_e32 v208, v210
	v_permlane16_swap_b32_e32 v209, v211
	v_lshlrev_b32_e32 v166, 16, v204
	v_and_b32_e32 v167, 0xffff0000, v204
	v_lshlrev_b32_e32 v168, 16, v205
	v_and_b32_e32 v169, 0xffff0000, v205
	v_lshlrev_b32_e32 v170, 16, v206
	v_and_b32_e32 v171, 0xffff0000, v206
	v_lshlrev_b32_e32 v172, 16, v207
	v_and_b32_e32 v173, 0xffff0000, v207
	v_lshlrev_b32_e32 v174, 16, v208
	v_and_b32_e32 v175, 0xffff0000, v208
	v_lshlrev_b32_e32 v176, 16, v209
	v_and_b32_e32 v177, 0xffff0000, v209
	v_lshlrev_b32_e32 v178, 16, v210
	v_and_b32_e32 v179, 0xffff0000, v210
	v_lshlrev_b32_e32 v180, 16, v211
	v_and_b32_e32 v181, 0xffff0000, v211
	v_pk_add_f32 v[30:31], v[30:31], v[166:167]
	v_pk_add_f32 v[32:33], v[32:33], v[168:169]
	v_pk_add_f32 v[26:27], v[26:27], v[170:171]
	v_pk_add_f32 v[28:29], v[28:29], v[172:173]
	v_pk_add_f32 v[22:23], v[22:23], v[174:175]
	v_pk_add_f32 v[24:25], v[24:25], v[176:177]
	v_pk_add_f32 v[18:19], v[18:19], v[178:179]
	v_pk_add_f32 v[20:21], v[20:21], v[180:181]
	v_cvt_pk_bf16_f32 v166, v30, v31
	v_cvt_pk_bf16_f32 v167, v32, v33
	v_cvt_pk_bf16_f32 v168, v26, v27
	v_cvt_pk_bf16_f32 v169, v28, v29
	v_cvt_pk_bf16_f32 v170, v22, v23
	v_cvt_pk_bf16_f32 v171, v24, v25
	v_cvt_pk_bf16_f32 v172, v18, v19
	v_cvt_pk_bf16_f32 v173, v20, v21
	v_add_u32_e32 v253, 0x50000, v252
	s_nop 1
	v_permlane16_swap_b32_e32 v166, v168
	v_permlane16_swap_b32_e32 v167, v169
	v_permlane16_swap_b32_e32 v170, v172
	v_permlane16_swap_b32_e32 v171, v173
	global_store_dwordx4 v253, v[166:169], s[14:15]
	global_store_dwordx4 v253, v[170:173], s[14:15] offset:256
	s_nop 1
	s_waitcnt vmcnt(12)
	v_permlane16_swap_b32_e32 v212, v214
	v_permlane16_swap_b32_e32 v213, v215
	v_permlane16_swap_b32_e32 v216, v218
	v_permlane16_swap_b32_e32 v217, v219
	v_lshlrev_b32_e32 v166, 16, v212
	v_and_b32_e32 v167, 0xffff0000, v212
	v_lshlrev_b32_e32 v168, 16, v213
	v_and_b32_e32 v169, 0xffff0000, v213
	v_lshlrev_b32_e32 v170, 16, v214
	v_and_b32_e32 v171, 0xffff0000, v214
	v_lshlrev_b32_e32 v172, 16, v215
	v_and_b32_e32 v173, 0xffff0000, v215
	v_lshlrev_b32_e32 v174, 16, v216
	v_and_b32_e32 v175, 0xffff0000, v216
	v_lshlrev_b32_e32 v176, 16, v217
	v_and_b32_e32 v177, 0xffff0000, v217
	v_lshlrev_b32_e32 v178, 16, v218
	v_and_b32_e32 v179, 0xffff0000, v218
	v_lshlrev_b32_e32 v180, 16, v219
	v_and_b32_e32 v181, 0xffff0000, v219
	v_pk_add_f32 v[14:15], v[14:15], v[166:167]
	v_pk_add_f32 v[16:17], v[16:17], v[168:169]
	v_pk_add_f32 v[10:11], v[10:11], v[170:171]
	v_pk_add_f32 v[12:13], v[12:13], v[172:173]
	v_pk_add_f32 v[6:7], v[6:7], v[174:175]
	v_pk_add_f32 v[8:9], v[8:9], v[176:177]
	v_pk_add_f32 v[2:3], v[2:3], v[178:179]
	v_pk_add_f32 v[4:5], v[4:5], v[180:181]
	v_cvt_pk_bf16_f32 v166, v14, v15
	v_cvt_pk_bf16_f32 v167, v16, v17
	v_cvt_pk_bf16_f32 v168, v10, v11
	v_cvt_pk_bf16_f32 v169, v12, v13
	v_cvt_pk_bf16_f32 v170, v6, v7
	v_cvt_pk_bf16_f32 v171, v8, v9
	v_cvt_pk_bf16_f32 v172, v2, v3
	v_cvt_pk_bf16_f32 v173, v4, v5
	v_add_u32_e32 v253, 0x58000, v252
	s_nop 1
	v_permlane16_swap_b32_e32 v166, v168
	v_permlane16_swap_b32_e32 v167, v169
	v_permlane16_swap_b32_e32 v170, v172
	v_permlane16_swap_b32_e32 v171, v173
	global_store_dwordx4 v253, v[166:169], s[14:15]
	global_store_dwordx4 v253, v[170:173], s[14:15] offset:256
	s_nop 1
	v_mul_f32_e32 v166, v126, v126
	v_mul_f32_e32 v167, v122, v122
	v_mul_f32_e32 v168, v118, v118
	v_mul_f32_e32 v169, v114, v114
	v_fmac_f32_e32 v166, v127, v127
	v_fmac_f32_e32 v167, v123, v123
	v_fmac_f32_e32 v168, v119, v119
	v_fmac_f32_e32 v169, v115, v115
	v_fmac_f32_e32 v166, v128, v128
	v_fmac_f32_e32 v167, v124, v124
	v_fmac_f32_e32 v168, v120, v120
	v_fmac_f32_e32 v169, v116, v116
	v_fmac_f32_e32 v166, v129, v129
	v_fmac_f32_e32 v167, v125, v125
	v_fmac_f32_e32 v168, v121, v121
	v_fmac_f32_e32 v169, v117, v117
	v_add_f32_e32 v166, v166, v167
	v_add_f32_e32 v168, v168, v169
; __device__ __forceinline__ unsigned pk_bf16(float lo, float hi) { const f32x2 v = {lo, hi}; const bf16x2_t b = __builtin_convertvector(v, bf16x2_t); return __builtin_bit_cast(unsigned, b); }
;     __device__ __forceinline__ void operator()(const f32x4 (&acc)[2][2][4][2], const pg8::Unit& u, int wr, int wc, int fr, int fq) const {
;     ...
;                     for (int n = 0; n < 2; ++n) { const f32x4 x4 = r4[bj][n] + acc[ai][bj][m][n];
;                         q += (x4[0] * x4[0] + x4[1] * x4[1]) + (x4[2] * x4[2] + x4[3] * x4[3]);
;                         u32x2 w; w.x = pk_bf16(x4[0], x4[1]); w.y = pk_bf16(x4[2], x4[3]); *(u32x2*)(XB + off + bj * 128 + n * 16) = w; }
;                 q += __shfl_xor(q, 16); q += __shfl_xor(q, 32);
;                 if (fq == 0) ssq[(size_t)row * 16 + u.pn * 4 + wc] = q;
	v_add_f32_e32 v178, v166, v168
	v_mov_b32_e32 v179, v178
	s_nop 0
	s_nop 0
	v_permlane32_swap_b32_e32 v179, v178
	v_add_f32_e32 v178, v178, v179
	v_mov_b32_e32 v179, v178
	s_nop 1
	v_permlane16_swap_b32_e32 v179, v178
	v_add_f32_e32 v178, v178, v179
	s_and_saveexec_b64 s[24:25], s[6:7]
	global_store_dword v189, v178, s[16:17]
	s_or_b64 exec, exec, s[24:25]
	v_mul_f32_e32 v170, v110, v110
	v_mul_f32_e32 v171, v106, v106
	v_mul_f32_e32 v172, v102, v102
	v_mul_f32_e32 v173, v98, v98
	v_fmac_f32_e32 v170, v111, v111
	v_fmac_f32_e32 v171, v107, v107
	v_fmac_f32_e32 v172, v103, v103
	v_fmac_f32_e32 v173, v99, v99
	v_fmac_f32_e32 v170, v112, v112
	v_fmac_f32_e32 v171, v108, v108
	v_fmac_f32_e32 v172, v104, v104
	v_fmac_f32_e32 v173, v100, v100
	v_fmac_f32_e32 v170, v113, v113
	v_fmac_f32_e32 v171, v109, v109
	v_fmac_f32_e32 v172, v105, v105
	v_fmac_f32_e32 v173, v101, v101
	v_add_f32_e32 v170, v170, v171
	v_add_f32_e32 v172, v172, v173
	v_add_f32_e32 v180, v170, v172
	v_mov_b32_e32 v181, v180
	s_nop 0
	s_nop 0
	v_permlane32_swap_b32_e32 v181, v180
	v_add_f32_e32 v180, v180, v181
	v_mov_b32_e32 v181, v180
	s_nop 1
	v_permlane16_swap_b32_e32 v181, v180
	v_add_f32_e32 v180, v180, v181
	s_and_saveexec_b64 s[24:25], s[6:7]
	global_store_dword v189, v180, s[16:17] offset:1024
	s_or_b64 exec, exec, s[24:25]
	v_mul_f32_e32 v166, v94, v94
	v_mul_f32_e32 v167, v90, v90
	v_mul_f32_e32 v168, v86, v86
	v_mul_f32_e32 v169, v82, v82
	v_fmac_f32_e32 v166, v95, v95
	v_fmac_f32_e32 v167, v91, v91
	v_fmac_f32_e32 v168, v87, v87
	v_fmac_f32_e32 v169, v83, v83
	v_fmac_f32_e32 v166, v96, v96
	v_fmac_f32_e32 v167, v92, v92
	v_fmac_f32_e32 v168, v88, v88
	v_fmac_f32_e32 v169, v84, v84
	v_fmac_f32_e32 v166, v97, v97
	v_fmac_f32_e32 v167, v93, v93
	v_fmac_f32_e32 v168, v89, v89
	v_fmac_f32_e32 v169, v85, v85
	v_add_f32_e32 v166, v166, v167
	v_add_f32_e32 v168, v168, v169
	v_add_f32_e32 v178, v166, v168
	v_mov_b32_e32 v179, v178
	s_nop 0
	s_nop 0
	v_permlane32_swap_b32_e32 v179, v178
	v_add_f32_e32 v178, v178, v179
	v_mov_b32_e32 v179, v178
	s_nop 1
	v_permlane16_swap_b32_e32 v179, v178
	v_add_f32_e32 v178, v178, v179
	s_and_saveexec_b64 s[24:25], s[6:7]
	global_store_dword v189, v178, s[16:17] offset:2048
	s_or_b64 exec, exec, s[24:25]
	v_mul_f32_e32 v170, v78, v78
	v_mul_f32_e32 v171, v74, v74
	v_mul_f32_e32 v172, v70, v70
	v_mul_f32_e32 v173, v66, v66
	v_fmac_f32_e32 v170, v79, v79
	v_fmac_f32_e32 v171, v75, v75
	v_fmac_f32_e32 v172, v71, v71
	v_fmac_f32_e32 v173, v67, v67
	v_fmac_f32_e32 v170, v80, v80
	v_fmac_f32_e32 v171, v76, v76
	v_fmac_f32_e32 v172, v72, v72
	v_fmac_f32_e32 v173, v68, v68
	v_fmac_f32_e32 v170, v81, v81
	v_fmac_f32_e32 v171, v77, v77
	v_fmac_f32_e32 v172, v73, v73
	v_fmac_f32_e32 v173, v69, v69
	v_add_f32_e32 v170, v170, v171
	v_add_f32_e32 v172, v172, v173
	v_add_f32_e32 v180, v170, v172
	v_mov_b32_e32 v181, v180
	s_nop 0
	s_nop 0
	v_permlane32_swap_b32_e32 v181, v180
	v_add_f32_e32 v180, v180, v181
	v_mov_b32_e32 v181, v180
	s_nop 1
	v_permlane16_swap_b32_e32 v181, v180
	v_add_f32_e32 v180, v180, v181
	s_and_saveexec_b64 s[24:25], s[6:7]
	global_store_dword v189, v180, s[16:17] offset:3072
	s_or_b64 exec, exec, s[24:25]
	v_mul_f32_e32 v166, v62, v62
	v_mul_f32_e32 v167, v58, v58
	v_mul_f32_e32 v168, v54, v54
	v_mul_f32_e32 v169, v50, v50
	v_fmac_f32_e32 v166, v63, v63
	v_fmac_f32_e32 v167, v59, v59
	v_fmac_f32_e32 v168, v55, v55
	v_fmac_f32_e32 v169, v51, v51
	v_fmac_f32_e32 v166, v64, v64
	v_fmac_f32_e32 v167, v60, v60
	v_fmac_f32_e32 v168, v56, v56
	v_fmac_f32_e32 v169, v52, v52
	v_fmac_f32_e32 v166, v65, v65
	v_fmac_f32_e32 v167, v61, v61
	v_fmac_f32_e32 v168, v57, v57
	v_fmac_f32_e32 v169, v53, v53
	v_add_f32_e32 v166, v166, v167
	v_add_f32_e32 v168, v168, v169
	v_add_f32_e32 v178, v166, v168
	v_mov_b32_e32 v179, v178
	v_add_u32_e32 v189, 0x2000, v189
	s_nop 0
	v_permlane32_swap_b32_e32 v179, v178
	v_add_f32_e32 v178, v178, v179
	v_mov_b32_e32 v179, v178
	s_nop 1
	v_permlane16_swap_b32_e32 v179, v178
	v_add_f32_e32 v178, v178, v179
	s_and_saveexec_b64 s[24:25], s[6:7]
	global_store_dword v189, v178, s[16:17]
	s_or_b64 exec, exec, s[24:25]
	v_mul_f32_e32 v170, v46, v46
	v_mul_f32_e32 v171, v42, v42
	v_mul_f32_e32 v172, v38, v38
	v_mul_f32_e32 v173, v34, v34
	v_fmac_f32_e32 v170, v47, v47
	v_fmac_f32_e32 v171, v43, v43
	v_fmac_f32_e32 v172, v39, v39
	v_fmac_f32_e32 v173, v35, v35
	v_fmac_f32_e32 v170, v48, v48
	v_fmac_f32_e32 v171, v44, v44
	v_fmac_f32_e32 v172, v40, v40
	v_fmac_f32_e32 v173, v36, v36
	v_fmac_f32_e32 v170, v49, v49
	v_fmac_f32_e32 v171, v45, v45
	v_fmac_f32_e32 v172, v41, v41
	v_fmac_f32_e32 v173, v37, v37
	v_add_f32_e32 v170, v170, v171
	v_add_f32_e32 v172, v172, v173
	v_add_f32_e32 v180, v170, v172
	v_mov_b32_e32 v181, v180
	s_nop 0
	s_nop 0
	v_permlane32_swap_b32_e32 v181, v180
	v_add_f32_e32 v180, v180, v181
	v_mov_b32_e32 v181, v180
	s_nop 1
	v_permlane16_swap_b32_e32 v181, v180
	v_add_f32_e32 v180, v180, v181
	s_and_saveexec_b64 s[24:25], s[6:7]
	global_store_dword v189, v180, s[16:17] offset:1024
	s_or_b64 exec, exec, s[24:25]
	v_mul_f32_e32 v166, v30, v30
	v_mul_f32_e32 v167, v26, v26
	v_mul_f32_e32 v168, v22, v22
	v_mul_f32_e32 v169, v18, v18
	v_fmac_f32_e32 v166, v31, v31
	v_fmac_f32_e32 v167, v27, v27
	v_fmac_f32_e32 v168, v23, v23
	v_fmac_f32_e32 v169, v19, v19
	v_fmac_f32_e32 v166, v32, v32
	v_fmac_f32_e32 v167, v28, v28
	v_fmac_f32_e32 v168, v24, v24
	v_fmac_f32_e32 v169, v20, v20
	v_fmac_f32_e32 v166, v33, v33
	v_fmac_f32_e32 v167, v29, v29
	v_fmac_f32_e32 v168, v25, v25
	v_fmac_f32_e32 v169, v21, v21
	v_add_f32_e32 v166, v166, v167
	v_add_f32_e32 v168, v168, v169
	v_add_f32_e32 v178, v166, v168
	v_mov_b32_e32 v179, v178
	s_nop 0
	s_nop 0
	v_permlane32_swap_b32_e32 v179, v178
	v_add_f32_e32 v178, v178, v179
	v_mov_b32_e32 v179, v178
	s_nop 1
	v_permlane16_swap_b32_e32 v179, v178
	v_add_f32_e32 v178, v178, v179
	s_and_saveexec_b64 s[24:25], s[6:7]
	global_store_dword v189, v178, s[16:17] offset:2048
	s_or_b64 exec, exec, s[24:25]
	v_mul_f32_e32 v170, v14, v14
	v_mul_f32_e32 v171, v10, v10
	v_mul_f32_e32 v172, v6, v6
	v_mul_f32_e32 v173, v2, v2
	v_fmac_f32_e32 v170, v15, v15
	v_fmac_f32_e32 v171, v11, v11
	v_fmac_f32_e32 v172, v7, v7
	v_fmac_f32_e32 v173, v3, v3
	v_fmac_f32_e32 v170, v16, v16
	v_fmac_f32_e32 v171, v12, v12
	v_fmac_f32_e32 v172, v8, v8
	v_fmac_f32_e32 v173, v4, v4
	v_fmac_f32_e32 v170, v17, v17
	v_fmac_f32_e32 v171, v13, v13
	v_fmac_f32_e32 v172, v9, v9
	v_fmac_f32_e32 v173, v5, v5
	v_add_f32_e32 v170, v170, v171
	v_add_f32_e32 v172, v172, v173
	v_add_f32_e32 v180, v170, v172
	v_mov_b32_e32 v181, v180
	s_nop 0
	s_nop 0
	v_permlane32_swap_b32_e32 v181, v180
	v_add_f32_e32 v180, v180, v181
	v_mov_b32_e32 v181, v180
	s_nop 1
	v_permlane16_swap_b32_e32 v181, v180
	v_add_f32_e32 v180, v180, v181
	s_and_saveexec_b64 s[24:25], s[6:7]
	global_store_dword v189, v180, s[16:17] offset:3072
	s_or_b64 exec, exec, s[24:25]
